# gdn_chunk: staging row loads issued back-to-back with one wait (was vmcnt(0) after each of 64); kk/qk loop reads all K_j fragments then one lgkmcnt(0)
# speedup vs baseline: 1.0336x; 1.0336x over previous
; DI float lo16(unsigned w) { return __uint_as_float(w << 16); }
; DI float silu(float x) { return x * __builtin_amdgcn_rcpf(1.f + fexp(-x)); }
; DI void gdn_chunk(CP c, int l, int item, float* sm) {
;     ...
;         for (int i0 = 0; i0 < 64; i0 += 32) {
;             unsigned xr[32];
; #pragma unroll
;             for (int k = 0; k < 32; ++k) xr[k] = (i0 + k < C) ? (unsigned)zr[(size_t)(i0 + k) * NZ1] : 0u;
; #pragma unroll
;             for (int k = 0; k < 32; ++k) { float y = 0.f;
;                 if (i0 + k < C) { const float x3 = lo16(xr[k]); y = silu(w0 * x0 + w1 * x1 + w2 * x2 + w3 * x3); x0 = x1; x1 = x2; x2 = x3; }
.LBB0_758:
	s_cmp_lt_u32 s0, s93
	v_mov_b32_e32 v78, 0
	s_cselect_b64 vcc, -1, 0
	s_cmp_ge_u32 s0, s93
	v_mov_b32_e32 v75, 0
	s_cbranch_scc1 .LBB0_760
	s_mul_i32 s14, s0, 0xf00
	v_lshl_add_u64 v[12:13], s[14:15], 1, v[6:7]
	global_load_ushort v75, v[12:13], off offset:2048
.LBB0_760:
	s_or_b32 s1, s0, 1
	s_cmp_lt_u32 s1, s93
	s_cselect_b64 s[6:7], -1, 0
	s_cmp_ge_u32 s1, s93
	s_cbranch_scc1 .LBB0_762
	s_mul_i32 s14, s1, 0xf00
	v_lshl_add_u64 v[12:13], s[14:15], 1, v[6:7]
	global_load_ushort v78, v[12:13], off offset:2048
.LBB0_762:
	s_or_b32 s1, s0, 2
	s_cmp_lt_u32 s1, s93
	v_mov_b32_e32 v72, 0
	s_cselect_b64 s[12:13], -1, 0
	s_cmp_ge_u32 s1, s93
	v_mov_b32_e32 v76, 0
	s_cbranch_scc1 .LBB0_764
	s_mul_i32 s14, s1, 0xf00
	v_lshl_add_u64 v[12:13], s[14:15], 1, v[6:7]
	global_load_ushort v76, v[12:13], off offset:2048
.LBB0_764:
	s_or_b32 s1, s0, 3
	s_cmp_lt_u32 s1, s93
	s_cselect_b64 s[96:97], -1, 0
	s_cmp_ge_u32 s1, s93
	s_cbranch_scc1 .LBB0_766
	s_mul_i32 s14, s1, 0xf00
	v_lshl_add_u64 v[12:13], s[14:15], 1, v[6:7]
	global_load_ushort v72, v[12:13], off offset:2048
.LBB0_766:
	s_or_b32 s1, s0, 4
	s_cmp_lt_u32 s1, s93
	v_mov_b32_e32 v66, 0
	s_cselect_b64 s[94:95], -1, 0
	s_cmp_ge_u32 s1, s93
	v_mov_b32_e32 v70, 0
	s_cbranch_scc1 .LBB0_768
	s_mul_i32 s14, s1, 0xf00
	v_lshl_add_u64 v[12:13], s[14:15], 1, v[6:7]
	global_load_ushort v70, v[12:13], off offset:2048
.LBB0_768:
	s_or_b32 s1, s0, 5
	s_cmp_lt_u32 s1, s93
	s_cselect_b64 s[88:89], -1, 0
	s_cmp_ge_u32 s1, s93
	s_cbranch_scc1 .LBB0_770
	s_mul_i32 s14, s1, 0xf00
	v_lshl_add_u64 v[12:13], s[14:15], 1, v[6:7]
	global_load_ushort v66, v[12:13], off offset:2048
.LBB0_770:
	s_or_b32 s1, s0, 6
	s_cmp_lt_u32 s1, s93
	v_mov_b32_e32 v60, 0
	s_cselect_b64 s[84:85], -1, 0
	s_cmp_ge_u32 s1, s93
	v_mov_b32_e32 v64, 0
	s_cbranch_scc1 .LBB0_772
	s_mul_i32 s14, s1, 0xf00
	v_lshl_add_u64 v[12:13], s[14:15], 1, v[6:7]
	global_load_ushort v64, v[12:13], off offset:2048
.LBB0_772:
	s_or_b32 s1, s0, 7
	s_cmp_lt_u32 s1, s93
	s_cselect_b64 s[82:83], -1, 0
	s_cmp_ge_u32 s1, s93
	s_cbranch_scc1 .LBB0_774
	s_mul_i32 s14, s1, 0xf00
	v_lshl_add_u64 v[12:13], s[14:15], 1, v[6:7]
	global_load_ushort v60, v[12:13], off offset:2048
.LBB0_774:
	s_or_b32 s1, s0, 8
	s_cmp_lt_u32 s1, s93
	v_mov_b32_e32 v56, 0
	s_cselect_b64 s[80:81], -1, 0
	s_cmp_ge_u32 s1, s93
	v_mov_b32_e32 v55, 0
	s_cbranch_scc1 .LBB0_776
	s_mul_i32 s14, s1, 0xf00
	v_lshl_add_u64 v[12:13], s[14:15], 1, v[6:7]
	global_load_ushort v55, v[12:13], off offset:2048
.LBB0_776:
	s_or_b32 s1, s0, 9
	s_cmp_lt_u32 s1, s93
	s_cselect_b64 s[78:79], -1, 0
	s_cmp_ge_u32 s1, s93
	s_cbranch_scc1 .LBB0_778
	s_mul_i32 s14, s1, 0xf00
	v_lshl_add_u64 v[12:13], s[14:15], 1, v[6:7]
	global_load_ushort v56, v[12:13], off offset:2048
.LBB0_778:
	s_or_b32 s1, s0, 10
	s_cmp_lt_u32 s1, s93
	v_mov_b32_e32 v50, 0
	s_cselect_b64 s[76:77], -1, 0
	s_cmp_ge_u32 s1, s93
	v_mov_b32_e32 v58, 0
	s_cbranch_scc1 .LBB0_780
	s_mul_i32 s14, s1, 0xf00
	v_lshl_add_u64 v[12:13], s[14:15], 1, v[6:7]
	global_load_ushort v58, v[12:13], off offset:2048
.LBB0_780:
	s_or_b32 s1, s0, 11
	s_cmp_lt_u32 s1, s93
	s_cselect_b64 s[74:75], -1, 0
	s_cmp_ge_u32 s1, s93
	s_cbranch_scc1 .LBB0_782
	s_mul_i32 s14, s1, 0xf00
	v_lshl_add_u64 v[12:13], s[14:15], 1, v[6:7]
	global_load_ushort v50, v[12:13], off offset:2048
.LBB0_782:
	s_or_b32 s1, s0, 12
	s_cmp_lt_u32 s1, s93
	v_mov_b32_e32 v48, 0
	s_cselect_b64 s[72:73], -1, 0
	s_cmp_ge_u32 s1, s93
	v_mov_b32_e32 v52, 0
	s_cbranch_scc1 .LBB0_784
	s_mul_i32 s14, s1, 0xf00
	v_lshl_add_u64 v[12:13], s[14:15], 1, v[6:7]
	global_load_ushort v52, v[12:13], off offset:2048
.LBB0_784:
	s_or_b32 s1, s0, 13
	s_cmp_lt_u32 s1, s93
	s_cselect_b64 s[68:69], -1, 0
	s_cmp_ge_u32 s1, s93
	s_cbranch_scc1 .LBB0_786
	s_mul_i32 s14, s1, 0xf00
	v_lshl_add_u64 v[12:13], s[14:15], 1, v[6:7]
	global_load_ushort v48, v[12:13], off offset:2048
.LBB0_786:
	s_or_b32 s1, s0, 14
	s_cmp_lt_u32 s1, s93
	v_mov_b32_e32 v44, 0
	s_cselect_b64 s[66:67], -1, 0
	s_cmp_ge_u32 s1, s93
	v_mov_b32_e32 v46, 0
	s_cbranch_scc1 .LBB0_788
	s_mul_i32 s14, s1, 0xf00
	v_lshl_add_u64 v[12:13], s[14:15], 1, v[6:7]
	global_load_ushort v46, v[12:13], off offset:2048
.LBB0_788:
	s_or_b32 s1, s0, 15
	s_cmp_lt_u32 s1, s93
	s_cselect_b64 s[64:65], -1, 0
	s_cmp_ge_u32 s1, s93
	s_cbranch_scc1 .LBB0_790
	s_mul_i32 s14, s1, 0xf00
	v_lshl_add_u64 v[12:13], s[14:15], 1, v[6:7]
	global_load_ushort v44, v[12:13], off offset:2048
.LBB0_790:
	s_or_b32 s1, s0, 16
	s_cmp_lt_u32 s1, s93
	v_mov_b32_e32 v40, 0
	s_cselect_b64 s[62:63], -1, 0
	s_cmp_ge_u32 s1, s93
	v_mov_b32_e32 v42, 0
	s_cbranch_scc1 .LBB0_792
	s_mul_i32 s14, s1, 0xf00
	v_lshl_add_u64 v[12:13], s[14:15], 1, v[6:7]
	global_load_ushort v42, v[12:13], off offset:2048
.LBB0_792:
	s_or_b32 s1, s0, 17
	s_cmp_lt_u32 s1, s93
	s_cselect_b64 s[60:61], -1, 0
	s_cmp_ge_u32 s1, s93
	s_cbranch_scc1 .LBB0_794
	s_mul_i32 s14, s1, 0xf00
	v_lshl_add_u64 v[12:13], s[14:15], 1, v[6:7]
	global_load_ushort v40, v[12:13], off offset:2048
.LBB0_794:
	s_or_b32 s1, s0, 18
	s_cmp_lt_u32 s1, s93
	v_mov_b32_e32 v31, 0
	s_cselect_b64 s[58:59], -1, 0
	s_cmp_ge_u32 s1, s93
	v_mov_b32_e32 v38, 0
	s_cbranch_scc1 .LBB0_796
	s_mul_i32 s14, s1, 0xf00
	v_lshl_add_u64 v[12:13], s[14:15], 1, v[6:7]
	global_load_ushort v38, v[12:13], off offset:2048
; DI float lo16(unsigned w) { return __uint_as_float(w << 16); }
; DI float silu(float x) { return x * __builtin_amdgcn_rcpf(1.f + fexp(-x)); }
; DI void gdn_chunk(CP c, int l, int item, float* sm) {
;     ...
;             for (int k = 0; k < 32; ++k) xr[k] = (i0 + k < C) ? (unsigned)zr[(size_t)(i0 + k) * NZ1] : 0u;
; #pragma unroll
;             for (int k = 0; k < 32; ++k) { float y = 0.f;
;                 if (i0 + k < C) { const float x3 = lo16(xr[k]); y = silu(w0 * x0 + w1 * x1 + w2 * x2 + w3 * x3); x0 = x1; x1 = x2; x2 = x3; }
.LBB0_796:
	s_or_b32 s1, s0, 19
	s_cmp_lt_u32 s1, s93
	s_cselect_b64 s[56:57], -1, 0
	s_cmp_ge_u32 s1, s93
	s_cbranch_scc1 .LBB0_798
	s_mul_i32 s14, s1, 0xf00
	v_lshl_add_u64 v[12:13], s[14:15], 1, v[6:7]
	global_load_ushort v31, v[12:13], off offset:2048
.LBB0_798:
	s_or_b32 s1, s0, 20
	s_cmp_lt_u32 s1, s93
	v_mov_b32_e32 v34, 0
	s_cselect_b64 s[54:55], -1, 0
	s_cmp_ge_u32 s1, s93
	v_mov_b32_e32 v36, 0
	s_cbranch_scc1 .LBB0_800
	s_mul_i32 s14, s1, 0xf00
	v_lshl_add_u64 v[12:13], s[14:15], 1, v[6:7]
	global_load_ushort v36, v[12:13], off offset:2048
.LBB0_800:
	s_or_b32 s1, s0, 21
	s_cmp_lt_u32 s1, s93
	s_cselect_b64 s[52:53], -1, 0
	s_cmp_ge_u32 s1, s93
	s_cbranch_scc1 .LBB0_802
	s_mul_i32 s14, s1, 0xf00
	v_lshl_add_u64 v[12:13], s[14:15], 1, v[6:7]
	global_load_ushort v34, v[12:13], off offset:2048
.LBB0_802:
	s_or_b32 s1, s0, 22
	s_cmp_lt_u32 s1, s93
	v_mov_b32_e32 v28, 0
	s_cselect_b64 s[50:51], -1, 0
	s_cmp_ge_u32 s1, s93
	v_mov_b32_e32 v32, 0
	s_cbranch_scc1 .LBB0_804
	s_mul_i32 s14, s1, 0xf00
	v_lshl_add_u64 v[12:13], s[14:15], 1, v[6:7]
	global_load_ushort v32, v[12:13], off offset:2048
.LBB0_804:
	s_or_b32 s1, s0, 23
	s_cmp_lt_u32 s1, s93
	s_cselect_b64 s[48:49], -1, 0
	s_cmp_ge_u32 s1, s93
	s_cbranch_scc1 .LBB0_806
	s_mul_i32 s14, s1, 0xf00
	v_lshl_add_u64 v[12:13], s[14:15], 1, v[6:7]
	global_load_ushort v28, v[12:13], off offset:2048
.LBB0_806:
	s_or_b32 s1, s0, 24
	s_cmp_lt_u32 s1, s93
	v_mov_b32_e32 v24, 0
	s_cselect_b64 s[44:45], -1, 0
	s_cmp_ge_u32 s1, s93
	v_mov_b32_e32 v26, 0
	s_cbranch_scc1 .LBB0_808
	s_mul_i32 s14, s1, 0xf00
	v_lshl_add_u64 v[12:13], s[14:15], 1, v[6:7]
	global_load_ushort v26, v[12:13], off offset:2048
.LBB0_808:
	s_or_b32 s1, s0, 25
	s_cmp_lt_u32 s1, s93
	s_cselect_b64 s[42:43], -1, 0
	s_cmp_ge_u32 s1, s93
	s_cbranch_scc1 .LBB0_810
	s_mul_i32 s14, s1, 0xf00
	v_lshl_add_u64 v[12:13], s[14:15], 1, v[6:7]
	global_load_ushort v24, v[12:13], off offset:2048
.LBB0_810:
	s_or_b32 s1, s0, 26
	s_cmp_lt_u32 s1, s93
	v_mov_b32_e32 v20, 0
	s_cselect_b64 s[40:41], -1, 0
	s_cmp_ge_u32 s1, s93
	v_mov_b32_e32 v22, 0
	s_cbranch_scc1 .LBB0_812
	s_mul_i32 s14, s1, 0xf00
	v_lshl_add_u64 v[12:13], s[14:15], 1, v[6:7]
	global_load_ushort v22, v[12:13], off offset:2048
.LBB0_812:
	s_or_b32 s1, s0, 27
	s_cmp_lt_u32 s1, s93
	s_cselect_b64 s[38:39], -1, 0
	s_cmp_ge_u32 s1, s93
	s_cbranch_scc1 .LBB0_814
	s_mul_i32 s14, s1, 0xf00
	v_lshl_add_u64 v[12:13], s[14:15], 1, v[6:7]
	global_load_ushort v20, v[12:13], off offset:2048
.LBB0_814:
	s_or_b32 s1, s0, 28
	s_cmp_lt_u32 s1, s93
	v_mov_b32_e32 v16, 0
	s_cselect_b64 s[36:37], -1, 0
	s_cmp_ge_u32 s1, s93
	v_mov_b32_e32 v18, 0
	s_cbranch_scc1 .LBB0_816
	s_mul_i32 s14, s1, 0xf00
	v_lshl_add_u64 v[12:13], s[14:15], 1, v[6:7]
	global_load_ushort v18, v[12:13], off offset:2048
.LBB0_816:
	s_or_b32 s1, s0, 29
	s_cmp_lt_u32 s1, s93
	s_cselect_b64 s[34:35], -1, 0
	s_cmp_ge_u32 s1, s93
	s_cbranch_scc1 .LBB0_818
	s_mul_i32 s14, s1, 0xf00
	v_lshl_add_u64 v[12:13], s[14:15], 1, v[6:7]
	global_load_ushort v16, v[12:13], off offset:2048
.LBB0_818:
	s_or_b32 s1, s0, 30
	s_cmp_lt_u32 s1, s93
	v_mov_b32_e32 v14, 0
	s_cselect_b64 s[30:31], -1, 0
	s_cmp_ge_u32 s1, s93
	v_mov_b32_e32 v13, 0
	s_cbranch_scc1 .LBB0_820
	s_mul_i32 s14, s1, 0xf00
	v_lshl_add_u64 v[12:13], s[14:15], 1, v[6:7]
	global_load_ushort v13, v[12:13], off offset:2048
.LBB0_820:
	s_or_b32 s1, s0, 31
	s_cmp_lt_u32 s1, s93
	s_cselect_b64 s[28:29], -1, 0
	s_cmp_ge_u32 s1, s93
	s_cbranch_scc1 .LBB0_822
	s_mul_i32 s14, s1, 0xf00
	v_lshl_add_u64 v[14:15], s[14:15], 1, v[6:7]
	global_load_ushort v14, v[14:15], off offset:2048
.LBB0_822:
	s_waitcnt vmcnt(0)
	v_lshlrev_b32_e32 v75, 16, v75
	v_lshlrev_b32_e32 v78, 16, v78
	v_lshlrev_b32_e32 v76, 16, v76
	v_lshlrev_b32_e32 v72, 16, v72
	v_lshlrev_b32_e32 v70, 16, v70
	v_lshlrev_b32_e32 v66, 16, v66
	v_lshlrev_b32_e32 v64, 16, v64
	v_lshlrev_b32_e32 v60, 16, v60
	v_lshlrev_b32_e32 v55, 16, v55
	v_lshlrev_b32_e32 v56, 16, v56
	v_lshlrev_b32_e32 v58, 16, v58
	v_lshlrev_b32_e32 v50, 16, v50
	v_lshlrev_b32_e32 v52, 16, v52
	v_lshlrev_b32_e32 v48, 16, v48
	v_lshlrev_b32_e32 v46, 16, v46
	v_lshlrev_b32_e32 v44, 16, v44
	v_lshlrev_b32_e32 v42, 16, v42
	v_lshlrev_b32_e32 v40, 16, v40
	v_lshlrev_b32_e32 v38, 16, v38
	v_lshlrev_b32_e32 v31, 16, v31
	v_lshlrev_b32_e32 v36, 16, v36
	v_lshlrev_b32_e32 v34, 16, v34
	v_lshlrev_b32_e32 v32, 16, v32
	v_lshlrev_b32_e32 v28, 16, v28
	v_lshlrev_b32_e32 v26, 16, v26
	v_lshlrev_b32_e32 v24, 16, v24
	v_lshlrev_b32_e32 v22, 16, v22
	v_lshlrev_b32_e32 v20, 16, v20
	v_lshlrev_b32_e32 v18, 16, v18
	v_lshlrev_b32_e32 v16, 16, v16
	v_lshlrev_b32_e32 v13, 16, v13
	v_lshlrev_b32_e32 v14, 16, v14
	s_andn2_b64 vcc, exec, vcc
	v_mov_b32_e32 v12, 0
	s_cbranch_vccnz .LBB0_824
	v_mov_b32_e32 v69, v62
	v_pk_mul_f32 v[68:69], v[2:3], v[68:69]
	v_mov_b32_e32 v74, v63
	v_pk_mul_f32 v[82:83], v[10:11], v[74:75]
	v_add_f32_e32 v15, v68, v69
	v_add_f32_e32 v15, v82, v15
	v_add_f32_e32 v15, v15, v83
	v_mul_f32_e32 v17, 0xbfb8aa3b, v15
	v_exp_f32_e32 v17, v17
	s_nop 0
	v_add_f32_e32 v17, 1.0, v17
	v_rcp_f32_e32 v17, v17
	s_nop 0
	v_mul_f32_e32 v17, v15, v17
	s_branch .LBB0_825

; DI void gdn_chunk(CP c, int l, int item, float* sm) {
;     ...
;         const int wv = __builtin_amdgcn_readfirstlane(wave); const int njj = (8 * wv < C) ? wv + 1 : 0;
;         if (njj > 0) {
;             for (int d4 = 0; d4 < 32; ++d4) { const f32x4 ki = *(const f32x4*)(Ks + i * 132 + d4 * 4), qi = *(const f32x4*)(Qs + i * 132 + d4 * 4);
; #pragma unroll
;                 for (int jj = 0; jj < 8; ++jj) if (jj < njj) { const f32x4 kj = *(const f32x4*)(Ks + (t7 + 8 * jj) * 132 + d4 * 4);
;                     kk[jj] += ki[0] * kj[0] + ki[1] * kj[1] + ki[2] * kj[2] + ki[3] * kj[3]; qk[jj] += qi[0] * kj[0] + qi[1] * kj[1] + qi[2] * kj[2] + qi[3] * kj[3]; } }
;         }
.LBB0_913:
	v_add_u32_e32 v6, s0, v0
	ds_read_b128 v[2:5], v6
	ds_read_b128 v[10:13], v6 offset:33792
	v_add_u32_e32 v35, s0, v15
	ds_read_b128 v[6:9], v35
	s_andn2_b64 vcc, exec, s[6:7]
	s_cbranch_vccnz .Lkk_ld_done
	ds_read_b128 v[40:43], v35 offset:4224
	s_andn2_b64 vcc, exec, s[12:13]
	s_cbranch_vccnz .Lkk_ld_done
	ds_read_b128 v[44:47], v35 offset:8448
	s_andn2_b64 vcc, exec, s[24:25]
	s_cbranch_vccnz .Lkk_ld_done
	ds_read_b128 v[48:51], v35 offset:12672
	s_andn2_b64 vcc, exec, s[26:27]
	s_cbranch_vccnz .Lkk_ld_done
	ds_read_b128 v[52:55], v35 offset:16896
	s_andn2_b64 vcc, exec, s[28:29]
	s_cbranch_vccnz .Lkk_ld_done
	ds_read_b128 v[56:59], v35 offset:21120
	s_andn2_b64 vcc, exec, s[30:31]
	s_cbranch_vccnz .Lkk_ld_done
	ds_read_b128 v[60:63], v35 offset:25344
	s_andn2_b64 vcc, exec, s[34:35]
	s_cbranch_vccnz .Lkk_ld_done
	ds_read_b128 v[64:67], v35 offset:29568
.Lkk_ld_done:
	s_waitcnt lgkmcnt(0)
	v_mov_b32_e32 v32, v2
	v_mov_b32_e32 v33, v11
	v_mov_b32_e32 v11, v3
	v_mov_b32_e32 v2, v12
	v_mov_b32_e32 v3, v4
	v_mov_b32_e32 v4, v13
	s_andn2_b64 vcc, exec, s[6:7]
	s_cbranch_vccnz .Lkk_j0
	v_pk_mul_f32 v[12:13], v[32:33], v[40:41]
	s_nop 0
	v_pk_fma_f32 v[12:13], v[10:11], v[40:41], v[12:13] op_sel:[0,0,1] op_sel_hi:[1,1,0]
	v_mov_b32_e32 v40, v43
	v_pk_fma_f32 v[12:13], v[2:3], v[42:43], v[12:13] op_sel_hi:[1,0,1]
	s_nop 0
	v_pk_fma_f32 v[12:13], v[4:5], v[40:41], v[12:13] op_sel_hi:[1,0,1]
	s_nop 0
	v_pk_add_f32 v[28:29], v[28:29], v[12:13]
	s_andn2_b64 vcc, exec, s[12:13]
	s_cbranch_vccnz .Lkk_j0
	v_pk_mul_f32 v[12:13], v[32:33], v[44:45]
	s_nop 0
	v_pk_fma_f32 v[12:13], v[10:11], v[44:45], v[12:13] op_sel:[0,0,1] op_sel_hi:[1,1,0]
	v_mov_b32_e32 v44, v47
	v_pk_fma_f32 v[12:13], v[2:3], v[46:47], v[12:13] op_sel_hi:[1,0,1]
	s_nop 0
	v_pk_fma_f32 v[12:13], v[4:5], v[44:45], v[12:13] op_sel_hi:[1,0,1]
	s_nop 0
	v_pk_add_f32 v[26:27], v[26:27], v[12:13]
	s_andn2_b64 vcc, exec, s[24:25]
	s_cbranch_vccnz .Lkk_j0
	v_pk_mul_f32 v[12:13], v[32:33], v[48:49]
	s_nop 0
	v_pk_fma_f32 v[12:13], v[10:11], v[48:49], v[12:13] op_sel:[0,0,1] op_sel_hi:[1,1,0]
	v_mov_b32_e32 v48, v51
	v_pk_fma_f32 v[12:13], v[2:3], v[50:51], v[12:13] op_sel_hi:[1,0,1]
	s_nop 0
	v_pk_fma_f32 v[12:13], v[4:5], v[48:49], v[12:13] op_sel_hi:[1,0,1]
	s_nop 0
	v_pk_add_f32 v[24:25], v[24:25], v[12:13]
	s_andn2_b64 vcc, exec, s[26:27]
	s_cbranch_vccnz .Lkk_j0
	v_pk_mul_f32 v[12:13], v[32:33], v[52:53]
	s_nop 0
	v_pk_fma_f32 v[12:13], v[10:11], v[52:53], v[12:13] op_sel:[0,0,1] op_sel_hi:[1,1,0]
	v_mov_b32_e32 v52, v55
	v_pk_fma_f32 v[12:13], v[2:3], v[54:55], v[12:13] op_sel_hi:[1,0,1]
	s_nop 0
	v_pk_fma_f32 v[12:13], v[4:5], v[52:53], v[12:13] op_sel_hi:[1,0,1]
	s_nop 0
	v_pk_add_f32 v[22:23], v[22:23], v[12:13]
	s_andn2_b64 vcc, exec, s[28:29]
	s_cbranch_vccnz .Lkk_j0
	v_pk_mul_f32 v[12:13], v[32:33], v[56:57]
	s_nop 0
	v_pk_fma_f32 v[12:13], v[10:11], v[56:57], v[12:13] op_sel:[0,0,1] op_sel_hi:[1,1,0]
	v_mov_b32_e32 v56, v59
	v_pk_fma_f32 v[12:13], v[2:3], v[58:59], v[12:13] op_sel_hi:[1,0,1]
	s_nop 0
	v_pk_fma_f32 v[12:13], v[4:5], v[56:57], v[12:13] op_sel_hi:[1,0,1]
	s_nop 0
	v_pk_add_f32 v[20:21], v[20:21], v[12:13]
	s_andn2_b64 vcc, exec, s[30:31]
	s_cbranch_vccnz .Lkk_j0
	v_pk_mul_f32 v[12:13], v[32:33], v[60:61]
	s_nop 0
	v_pk_fma_f32 v[12:13], v[10:11], v[60:61], v[12:13] op_sel:[0,0,1] op_sel_hi:[1,1,0]
	v_mov_b32_e32 v60, v63
	v_pk_fma_f32 v[12:13], v[2:3], v[62:63], v[12:13] op_sel_hi:[1,0,1]
	s_nop 0
	v_pk_fma_f32 v[12:13], v[4:5], v[60:61], v[12:13] op_sel_hi:[1,0,1]
	s_nop 0
	v_pk_add_f32 v[18:19], v[18:19], v[12:13]
	s_andn2_b64 vcc, exec, s[34:35]
	s_cbranch_vccnz .Lkk_j0
	v_pk_mul_f32 v[12:13], v[32:33], v[64:65]
	s_nop 0
	v_pk_fma_f32 v[12:13], v[10:11], v[64:65], v[12:13] op_sel:[0,0,1] op_sel_hi:[1,1,0]
	v_mov_b32_e32 v64, v67
	v_pk_fma_f32 v[12:13], v[2:3], v[66:67], v[12:13] op_sel_hi:[1,0,1]
	s_nop 0
	v_pk_fma_f32 v[12:13], v[4:5], v[64:65], v[12:13] op_sel_hi:[1,0,1]
	s_nop 0
	v_pk_add_f32 v[16:17], v[16:17], v[12:13]
.Lkk_j0:
	v_pk_mul_f32 v[12:13], v[32:33], v[6:7]
	s_add_i32 s0, s0, 16
	v_pk_fma_f32 v[6:7], v[10:11], v[6:7], v[12:13] op_sel:[0,0,1] op_sel_hi:[1,1,0]
	s_cmpk_lg_i32 s0, 0x200
	v_pk_fma_f32 v[2:3], v[2:3], v[8:9], v[6:7] op_sel_hi:[1,0,1]
	v_mov_b32_e32 v6, v9
	v_pk_fma_f32 v[2:3], v[4:5], v[6:7], v[2:3] op_sel_hi:[1,0,1]
	s_nop 0
	v_pk_add_f32 v[30:31], v[30:31], v[2:3]
	s_cbranch_scc1 .LBB0_913
	s_branch .LBB0_928
